# ping-pong attention: s_setprio 1 during each wave's compute segment (dropped at its end) instead of a static raise for waves 4-7
# baseline (speedup 1.0000x reference)
; #define LAS __attribute__((address_space(3)))
; DI s16x4 vtr(const LAS char* p) { return __builtin_bit_cast(s16x4, __builtin_amdgcn_ds_read_tr16_b64_v4i16((LAS v4i16_t*)p)); }
; DI void attn_qk(const LAS char* kb, const bf16x8 (&qf)[4], bf16x8 (&pf)[4], float& l) {
;     f32x16 zero;
; #pragma unroll
;     for (int i = 0; i < 16; ++i) zero[i] = 0.f;
;     bf16x8 k0[4], k1[4];
; #pragma unroll
;     for (int s = 0; s < 4; ++s) k0[s] = *(const LAS bf16x8*)(kb + 32 * s);
; #pragma unroll
;     for (int s = 0; s < 4; ++s) k1[s] = *(const LAS bf16x8*)(kb + 32 * KRS + 32 * s);
;     f32x16 st0 = MFMA32(k0[0], qf[0], zero), st1 = MFMA32(k1[0], qf[0], zero);
; #pragma unroll
;     for (int s = 1; s < 4; ++s) { st0 = MFMA32(k0[s], qf[s], st0); st1 = MFMA32(k1[s], qf[s], st1); }
;     SGB(0x100, 8); SGB(0x008, 8);
;     float sum = 0.f;
; #pragma unroll
;     for (int i = 0; i < 16; ++i) { const float e = __builtin_amdgcn_exp2f(st0[i]); st0[i] = e; sum += e; }
;     pf[0] = pack8(st0, 0); pf[1] = pack8(st0, 1);
; #pragma unroll
;     for (int i = 0; i < 16; ++i) { const float e = __builtin_amdgcn_exp2f(st1[i]); st1[i] = e; sum += e; }
;     pf[2] = pack8(st1, 0); pf[3] = pack8(st1, 1);
;     l += sum;
; }
; DI void attn_pv(const LAS char* vb, const bf16x8 (&pf)[4], f32x16 (&O)[4]) {
;     s16x4 va[8], vc[8];
; #pragma unroll
;     for (int ks = 0; ks < 4; ++ks) { va[2 * ks] = vtr(vb + ks * 16 * VRS); va[2 * ks + 1] = vtr(vb + (ks * 16 + 8) * VRS); }
; #pragma unroll
;     for (int ks = 0; ks < 4; ++ks) { vc[2 * ks] = vtr(vb + ks * 16 * VRS + 64); vc[2 * ks + 1] = vtr(vb + (ks * 16 + 8) * VRS + 64); }
; DI void attn_unit(const Params& p, LAS unsigned char* ldsu, int kind, int b, int h, int u, float lam) {
;     ...
;         auto stage = [&](int t) { if (t >= ntl) t = ntl - 1; const int row0 = t == 0 ? ROW_M : b * SEQ + (t - 1) * 64;
;             dma_tile(lds + (t & 3) * SLOT_B, KB + (size_t)row0 * 512 + hc, VB + (size_t)row0 * 512 + hc, poff, wid); };
;         stage(0); stage(1); stage(2);
;         asm volatile("s_waitcnt vmcnt(10)" ::: "memory");
;         __syncthreads();
;         for (int t = 0; t < ntl; ++t) {
;             stage(t + 3);
;             const LAS char* sp = lds + (t & 3) * SLOT_B;
;             if (t <= my_last) { bf16x8 pf[4]; attn_qk(sp + kboff, qf, pf, l); attn_pv(sp + vboff, pf, O); }
;             BAR_LANDED();
.LBB0_745:
	s_and_b64 vcc, exec, s[0:1]
	s_cbranch_vccz .LattnB
	s_add_i32 s22, s21, 3
	s_min_i32 s24, s22, s6
	s_lshl_b32 s22, s24, 6
	s_add_i32 s22, s17, s22
	s_and_b32 s24, s24, 3
	s_ashr_i32 s23, s22, 31
	s_mul_i32 s24, s24, 0x9400
	s_lshl_b64 s[22:23], s[22:23], 10
	s_add_u32 s25, s16, s22
	s_addc_u32 s26, s18, s23
	s_add_u32 s27, s19, s22
	s_addc_u32 s34, s20, s23
	s_cmp_gt_i32 s21, s29
	s_cbranch_scc1 .LattnA_skip
	s_and_b32 s35, s21, 3
	s_mul_i32 s35, s35, 0x9400
	v_add_u32_e32 v0, s35, v174
	v_add_u32_e32 v14, s35, v134
	ds_read_b128 v[2:5], v0
	ds_read_b128 v[6:9], v0 offset:32
	ds_read_b128 v[10:13], v0 offset:64
	ds_read_b128 v[136:139], v0 offset:96
	ds_read_b128 v[140:143], v0 offset:8704
	ds_read_b128 v[144:147], v0 offset:8736
	ds_read_b128 v[148:151], v0 offset:8768
	ds_read_b128 v[196:199], v0 offset:8800
	ds_read_b64_tr_b16 v[200:201], v14 offset:17408
	ds_read_b64_tr_b16 v[202:203], v14 offset:19968
	ds_read_b64_tr_b16 v[204:205], v14 offset:17472
	ds_read_b64_tr_b16 v[206:207], v14 offset:20032
	ds_read_b64_tr_b16 v[208:209], v14 offset:17536
	ds_read_b64_tr_b16 v[210:211], v14 offset:20096
	ds_read_b64_tr_b16 v[212:213], v14 offset:17600
	ds_read_b64_tr_b16 v[214:215], v14 offset:20160
	ds_read_b64_tr_b16 v[216:217], v14 offset:22528
	ds_read_b64_tr_b16 v[218:219], v14 offset:25088
	ds_read_b64_tr_b16 v[220:221], v14 offset:22592
	ds_read_b64_tr_b16 v[222:223], v14 offset:25152
	ds_read_b64_tr_b16 v[224:225], v14 offset:22656
	ds_read_b64_tr_b16 v[226:227], v14 offset:25216
	ds_read_b64_tr_b16 v[228:229], v14 offset:22720
	ds_read_b64_tr_b16 v[230:231], v14 offset:25280
	ds_read_b64_tr_b16 v[232:233], v14 offset:27648
	ds_read_b64_tr_b16 v[234:235], v14 offset:30208
	ds_read_b64_tr_b16 v[236:237], v14 offset:27712
	ds_read_b64_tr_b16 v[238:239], v14 offset:30272
	ds_read_b64_tr_b16 v[240:241], v14 offset:27776
	ds_read_b64_tr_b16 v[242:243], v14 offset:30336
	ds_read_b64_tr_b16 v[244:245], v14 offset:27840
	ds_read_b64_tr_b16 v[246:247], v14 offset:30400
	ds_read_b64_tr_b16 v[248:249], v14 offset:32768
	ds_read_b64_tr_b16 v[250:251], v14 offset:35328
	ds_read_b64_tr_b16 v[156:157], v14 offset:32832
	ds_read_b64_tr_b16 v[158:159], v14 offset:35392
	ds_read_b64_tr_b16 v[160:161], v14 offset:32896
	ds_read_b64_tr_b16 v[162:163], v14 offset:35456
	ds_read_b64_tr_b16 v[164:165], v14 offset:32960
	ds_read_b64_tr_b16 v[166:167], v14 offset:35520
	s_and_b64 s[22:23], s[0:1], exec
	s_cselect_b32 s23, s26, s34
	s_cselect_b32 s22, s25, s27
	s_add_i32 s35, s24, s7
	s_mov_b32 m0, s35
	s_nop 0
	global_load_lds_dwordx4 v132, s[22:23]
	s_add_i32 s35, s24, s10
	s_addk_i32 s35, 0x400
	s_mov_b32 m0, s35
	s_nop 0
	global_load_lds_dwordx4 v131, s[22:23]
	s_and_b64 s[22:23], exec, s[8:9]
	s_cselect_b32 s23, s26, s34
	s_cselect_b32 s22, s25, s27
	s_add_i32 s35, s24, s11
	s_addk_i32 s35, 0x800
	s_mov_b32 m0, s35
	s_nop 0
	global_load_lds_dwordx4 v130, s[22:23]
	s_add_i32 s35, s24, s12
	s_addk_i32 s35, 0xc00
	s_mov_b32 m0, s35
	s_nop 0
	global_load_lds_dwordx4 v129, s[22:23]
	s_add_i32 s35, s24, s13
	s_addk_i32 s35, 0x1000
	s_mov_b32 m0, s35
	s_nop 0
	global_load_lds_dwordx4 v133, s[22:23]
	s_waitcnt lgkmcnt(0)
	s_barrier
; #define LAS __attribute__((address_space(3)))
; DI s16x4 vtr(const LAS char* p) { return __builtin_bit_cast(s16x4, __builtin_amdgcn_ds_read_tr16_b64_v4i16((LAS v4i16_t*)p)); }
; DI void attn_qk(const LAS char* kb, const bf16x8 (&qf)[4], bf16x8 (&pf)[4], float& l) {
;     ...
;     f32x16 st0 = MFMA32(k0[0], qf[0], zero), st1 = MFMA32(k1[0], qf[0], zero);
; #pragma unroll
;     for (int s = 1; s < 4; ++s) { st0 = MFMA32(k0[s], qf[s], st0); st1 = MFMA32(k1[s], qf[s], st1); }
;     SGB(0x100, 8); SGB(0x008, 8);
;     float sum = 0.f;
; #pragma unroll
;     for (int i = 0; i < 16; ++i) { const float e = __builtin_amdgcn_exp2f(st0[i]); st0[i] = e; sum += e; }
;     pf[0] = pack8(st0, 0); pf[1] = pack8(st0, 1);
; #pragma unroll
;     for (int i = 0; i < 16; ++i) { const float e = __builtin_amdgcn_exp2f(st1[i]); st1[i] = e; sum += e; }
;     pf[2] = pack8(st1, 0); pf[3] = pack8(st1, 1);
;     l += sum;
; }
; DI void attn_pv(const LAS char* vb, const bf16x8 (&pf)[4], f32x16 (&O)[4]) {
;     s16x4 va[8], vc[8];
; #pragma unroll
;     for (int ks = 0; ks < 4; ++ks) { va[2 * ks] = vtr(vb + ks * 16 * VRS); va[2 * ks + 1] = vtr(vb + (ks * 16 + 8) * VRS); }
; #pragma unroll
;     for (int ks = 0; ks < 4; ++ks) { vc[2 * ks] = vtr(vb + ks * 16 * VRS + 64); vc[2 * ks + 1] = vtr(vb + (ks * 16 + 8) * VRS + 64); }
; #pragma unroll
;     for (int ks = 0; ks < 4; ++ks) O[0] = MFMA32(cat4(va[2 * ks], va[2 * ks + 1]), pf[ks], O[0]);
; #pragma unroll
;     for (int ks = 0; ks < 4; ++ks) { va[2 * ks] = vtr(vb + ks * 16 * VRS + 128); va[2 * ks + 1] = vtr(vb + (ks * 16 + 8) * VRS + 128); }
;     SGB(0x100, 16); SGB(0x008, 4); SGB(0x100, 8);
; #pragma unroll
;     for (int ks = 0; ks < 4; ++ks) O[1] = MFMA32(cat4(vc[2 * ks], vc[2 * ks + 1]), pf[ks], O[1]);
; #pragma unroll
;     for (int ks = 0; ks < 4; ++ks) { vc[2 * ks] = vtr(vb + ks * 16 * VRS + 192); vc[2 * ks + 1] = vtr(vb + (ks * 16 + 8) * VRS + 192); }
;     SGB(0x008, 4); SGB(0x100, 8);
; #pragma unroll
;     for (int ks = 0; ks < 4; ++ks) O[2] = MFMA32(cat4(va[2 * ks], va[2 * ks + 1]), pf[ks], O[2]);
;     SGB(0x008, 4);
; #pragma unroll
;     for (int ks = 0; ks < 4; ++ks) O[3] = MFMA32(cat4(vc[2 * ks], vc[2 * ks + 1]), pf[ks], O[3]);
;     SGB(0x008, 4);
; }
; DI void attn_unit(const Params& p, LAS unsigned char* ldsu, int kind, int b, int h, int u, float lam) {
;     ...
;             BAR_LANDED();
	s_setprio 1
	v_mfma_f32_32x32x16_bf16 v[96:111], v[2:5], v[112:115], 0
	v_mfma_f32_32x32x16_bf16 v[96:111], v[6:9], v[116:119], v[96:111]
	v_mfma_f32_32x32x16_bf16 v[96:111], v[10:13], v[120:123], v[96:111]
	v_mfma_f32_32x32x16_bf16 v[96:111], v[136:139], v[124:127], v[96:111]
	s_nop 7
	s_nop 2
	v_mfma_f32_32x32x16_bf16 v[80:95], v[140:143], v[112:115], 0
	v_exp_f32_e32 v96, v96
	v_exp_f32_e32 v97, v97
	s_nop 0
	v_add_f32_e32 v15, v96, v97
	v_mfma_f32_32x32x16_bf16 v[80:95], v[144:147], v[116:119], v[80:95]
	v_exp_f32_e32 v98, v98
	v_exp_f32_e32 v99, v99
	v_cvt_pk_bf16_f32 v96, v96, v97
	v_add_f32_e32 v15, v98, v15
	v_mfma_f32_32x32x16_bf16 v[80:95], v[148:151], v[120:123], v[80:95]
	v_exp_f32_e32 v100, v100
	v_exp_f32_e32 v101, v101
	v_cvt_pk_bf16_f32 v97, v98, v99
	v_add_f32_e32 v15, v99, v15
	v_mfma_f32_32x32x16_bf16 v[80:95], v[196:199], v[124:127], v[80:95]
	v_exp_f32_e32 v102, v102
	v_exp_f32_e32 v103, v103
	v_cvt_pk_bf16_f32 v98, v100, v101
	v_cvt_pk_bf16_f32 v99, v102, v103
	s_nop 1
	v_mfma_f32_32x32x16_bf16 v[64:79], v[200:203], v[96:99], v[64:79]
	v_exp_f32_e32 v104, v104
	v_exp_f32_e32 v105, v105
	v_add_f32_e32 v15, v104, v15
	v_add_f32_e32 v15, v105, v15
	v_mfma_f32_32x32x16_bf16 v[48:63], v[204:207], v[96:99], v[48:63]
	v_exp_f32_e32 v106, v106
	v_exp_f32_e32 v107, v107
	v_cvt_pk_bf16_f32 v104, v104, v105
	v_add_f32_e32 v15, v106, v15
	v_mfma_f32_32x32x16_bf16 v[32:47], v[208:211], v[96:99], v[32:47]
	v_exp_f32_e32 v108, v108
	v_exp_f32_e32 v109, v109
	v_cvt_pk_bf16_f32 v105, v106, v107
	v_add_f32_e32 v15, v107, v15
	v_mfma_f32_32x32x16_bf16 v[16:31], v[212:215], v[96:99], v[16:31]
	v_exp_f32_e32 v110, v110
	v_exp_f32_e32 v111, v111
	v_cvt_pk_bf16_f32 v106, v108, v109
	v_cvt_pk_bf16_f32 v107, v110, v111
	s_nop 1
	v_mfma_f32_32x32x16_bf16 v[64:79], v[216:219], v[104:107], v[64:79]
	v_exp_f32_e32 v80, v80
	v_exp_f32_e32 v81, v81
	v_add_f32_e32 v15, v80, v15
	v_add_f32_e32 v15, v81, v15
	v_mfma_f32_32x32x16_bf16 v[48:63], v[220:223], v[104:107], v[48:63]
	v_exp_f32_e32 v82, v82
	v_exp_f32_e32 v83, v83
	v_cvt_pk_bf16_f32 v80, v80, v81
	v_add_f32_e32 v15, v82, v15
	v_mfma_f32_32x32x16_bf16 v[32:47], v[224:227], v[104:107], v[32:47]
	v_exp_f32_e32 v84, v84
	v_exp_f32_e32 v85, v85
	v_cvt_pk_bf16_f32 v81, v82, v83
	v_add_f32_e32 v15, v83, v15
	v_mfma_f32_32x32x16_bf16 v[16:31], v[228:231], v[104:107], v[16:31]
	v_exp_f32_e32 v86, v86
	v_exp_f32_e32 v87, v87
	v_cvt_pk_bf16_f32 v82, v84, v85
	v_cvt_pk_bf16_f32 v83, v86, v87
	s_nop 1
	v_mfma_f32_32x32x16_bf16 v[64:79], v[232:235], v[80:83], v[64:79]
	v_exp_f32_e32 v88, v88
	v_exp_f32_e32 v89, v89
	v_add_f32_e32 v15, v88, v15
	v_add_f32_e32 v15, v89, v15
	v_mfma_f32_32x32x16_bf16 v[48:63], v[236:239], v[80:83], v[48:63]
	v_exp_f32_e32 v90, v90
	v_exp_f32_e32 v91, v91
	v_cvt_pk_bf16_f32 v88, v88, v89
	v_add_f32_e32 v15, v90, v15
	v_mfma_f32_32x32x16_bf16 v[32:47], v[240:243], v[80:83], v[32:47]
	v_exp_f32_e32 v92, v92
	v_exp_f32_e32 v93, v93
	v_cvt_pk_bf16_f32 v89, v90, v91
	v_add_f32_e32 v15, v91, v15
	v_mfma_f32_32x32x16_bf16 v[16:31], v[244:247], v[80:83], v[16:31]
	v_exp_f32_e32 v94, v94
	v_exp_f32_e32 v95, v95
	v_cvt_pk_bf16_f32 v90, v92, v93
	v_cvt_pk_bf16_f32 v91, v94, v95
	s_nop 1
	v_mfma_f32_32x32x16_bf16 v[64:79], v[248:251], v[88:91], v[64:79]
	v_add_f32_e32 v15, v100, v15
	v_add_f32_e32 v15, v101, v15
	v_add_f32_e32 v15, v102, v15
	v_add_f32_e32 v15, v103, v15
	v_mfma_f32_32x32x16_bf16 v[48:63], v[156:159], v[88:91], v[48:63]
	v_add_f32_e32 v15, v108, v15
	v_add_f32_e32 v15, v109, v15
	v_add_f32_e32 v15, v110, v15
	v_add_f32_e32 v15, v111, v15
	v_mfma_f32_32x32x16_bf16 v[32:47], v[160:163], v[88:91], v[32:47]
	v_add_f32_e32 v15, v84, v15
	v_add_f32_e32 v15, v85, v15
	v_add_f32_e32 v15, v86, v15
	v_add_f32_e32 v15, v87, v15
	v_mfma_f32_32x32x16_bf16 v[16:31], v[164:167], v[88:91], v[16:31]
	v_add_f32_e32 v15, v92, v15
	v_add_f32_e32 v15, v93, v15
	v_add_f32_e32 v15, v94, v15
	v_add_f32_e32 v15, v95, v15
	v_add_f32_e32 v175, v175, v15
	s_setprio 0
	s_waitcnt vmcnt(10)
	s_barrier
	s_branch .LBB0_744

; #define LAS __attribute__((address_space(3)))
; DI s16x4 vtr(const LAS char* p) { return __builtin_bit_cast(s16x4, __builtin_amdgcn_ds_read_tr16_b64_v4i16((LAS v4i16_t*)p)); }
; DI void attn_qk(const LAS char* kb, const bf16x8 (&qf)[4], bf16x8 (&pf)[4], float& l) {
;     f32x16 zero;
; #pragma unroll
;     for (int i = 0; i < 16; ++i) zero[i] = 0.f;
;     bf16x8 k0[4], k1[4];
; #pragma unroll
;     for (int s = 0; s < 4; ++s) k0[s] = *(const LAS bf16x8*)(kb + 32 * s);
; #pragma unroll
;     for (int s = 0; s < 4; ++s) k1[s] = *(const LAS bf16x8*)(kb + 32 * KRS + 32 * s);
;     f32x16 st0 = MFMA32(k0[0], qf[0], zero), st1 = MFMA32(k1[0], qf[0], zero);
; #pragma unroll
;     for (int s = 1; s < 4; ++s) { st0 = MFMA32(k0[s], qf[s], st0); st1 = MFMA32(k1[s], qf[s], st1); }
;     SGB(0x100, 8); SGB(0x008, 8);
;     float sum = 0.f;
; #pragma unroll
;     for (int i = 0; i < 16; ++i) { const float e = __builtin_amdgcn_exp2f(st0[i]); st0[i] = e; sum += e; }
;     pf[0] = pack8(st0, 0); pf[1] = pack8(st0, 1);
; #pragma unroll
;     for (int i = 0; i < 16; ++i) { const float e = __builtin_amdgcn_exp2f(st1[i]); st1[i] = e; sum += e; }
;     pf[2] = pack8(st1, 0); pf[3] = pack8(st1, 1);
;     l += sum;
; }
; DI void attn_pv(const LAS char* vb, const bf16x8 (&pf)[4], f32x16 (&O)[4]) {
;     s16x4 va[8], vc[8];
; #pragma unroll
;     for (int ks = 0; ks < 4; ++ks) { va[2 * ks] = vtr(vb + ks * 16 * VRS); va[2 * ks + 1] = vtr(vb + (ks * 16 + 8) * VRS); }
; #pragma unroll
;     for (int ks = 0; ks < 4; ++ks) { vc[2 * ks] = vtr(vb + ks * 16 * VRS + 64); vc[2 * ks + 1] = vtr(vb + (ks * 16 + 8) * VRS + 64); }
; DI void attn_unit(const Params& p, LAS unsigned char* ldsu, int kind, int b, int h, int u, float lam) {
;     ...
;         auto stage = [&](int t) { if (t >= ntl) t = ntl - 1; const int row0 = t == 0 ? ROW_M : b * SEQ + (t - 1) * 64;
;             dma_tile(lds + (t & 3) * SLOT_B, KB + (size_t)row0 * 512 + hc, VB + (size_t)row0 * 512 + hc, poff, wid); };
;         stage(0); stage(1); stage(2);
;         asm volatile("s_waitcnt vmcnt(10)" ::: "memory");
;         __syncthreads();
;         for (int t = 0; t < ntl; ++t) {
;             stage(t + 3);
;             const LAS char* sp = lds + (t & 3) * SLOT_B;
;             if (t <= my_last) { bf16x8 pf[4]; attn_qk(sp + kboff, qf, pf, l); attn_pv(sp + vboff, pf, O); }
;             BAR_LANDED();
.LattnB:
	s_add_i32 s22, s21, 3
	s_min_i32 s24, s22, s6
	s_lshl_b32 s22, s24, 6
	s_add_i32 s22, s17, s22
	s_and_b32 s24, s24, 3
	s_ashr_i32 s23, s22, 31
	s_mul_i32 s24, s24, 0x9400
	s_lshl_b64 s[22:23], s[22:23], 10
	s_add_u32 s25, s16, s22
	s_addc_u32 s26, s18, s23
	s_add_u32 s27, s19, s22
	s_addc_u32 s34, s20, s23
	s_cmp_gt_i32 s21, s29
	s_cbranch_scc1 .LattnB_skip
	s_and_b32 s35, s21, 3
	s_mul_i32 s35, s35, 0x9400
	v_add_u32_e32 v0, s35, v174
	v_add_u32_e32 v14, s35, v134
	ds_read_b128 v[2:5], v0
	ds_read_b128 v[6:9], v0 offset:32
	ds_read_b128 v[10:13], v0 offset:64
	ds_read_b128 v[136:139], v0 offset:96
	ds_read_b128 v[140:143], v0 offset:8704
	ds_read_b128 v[144:147], v0 offset:8736
	ds_read_b128 v[148:151], v0 offset:8768
	ds_read_b128 v[196:199], v0 offset:8800
	ds_read_b64_tr_b16 v[200:201], v14 offset:17408
	ds_read_b64_tr_b16 v[202:203], v14 offset:19968
	ds_read_b64_tr_b16 v[204:205], v14 offset:17472
	ds_read_b64_tr_b16 v[206:207], v14 offset:20032
	ds_read_b64_tr_b16 v[208:209], v14 offset:17536
	ds_read_b64_tr_b16 v[210:211], v14 offset:20096
	ds_read_b64_tr_b16 v[212:213], v14 offset:17600
	ds_read_b64_tr_b16 v[214:215], v14 offset:20160
	ds_read_b64_tr_b16 v[216:217], v14 offset:22528
	ds_read_b64_tr_b16 v[218:219], v14 offset:25088
	ds_read_b64_tr_b16 v[220:221], v14 offset:22592
	ds_read_b64_tr_b16 v[222:223], v14 offset:25152
	ds_read_b64_tr_b16 v[224:225], v14 offset:22656
	ds_read_b64_tr_b16 v[226:227], v14 offset:25216
	ds_read_b64_tr_b16 v[228:229], v14 offset:22720
	ds_read_b64_tr_b16 v[230:231], v14 offset:25280
	ds_read_b64_tr_b16 v[232:233], v14 offset:27648
	ds_read_b64_tr_b16 v[234:235], v14 offset:30208
	ds_read_b64_tr_b16 v[236:237], v14 offset:27712
	ds_read_b64_tr_b16 v[238:239], v14 offset:30272
	ds_read_b64_tr_b16 v[240:241], v14 offset:27776
	ds_read_b64_tr_b16 v[242:243], v14 offset:30336
	ds_read_b64_tr_b16 v[244:245], v14 offset:27840
	ds_read_b64_tr_b16 v[246:247], v14 offset:30400
	ds_read_b64_tr_b16 v[248:249], v14 offset:32768
	ds_read_b64_tr_b16 v[250:251], v14 offset:35328
	ds_read_b64_tr_b16 v[156:157], v14 offset:32832
	ds_read_b64_tr_b16 v[158:159], v14 offset:35392
	ds_read_b64_tr_b16 v[160:161], v14 offset:32896
	ds_read_b64_tr_b16 v[162:163], v14 offset:35456
	ds_read_b64_tr_b16 v[164:165], v14 offset:32960
	ds_read_b64_tr_b16 v[166:167], v14 offset:35520
	s_and_b64 s[22:23], s[0:1], exec
	s_cselect_b32 s23, s26, s34
	s_cselect_b32 s22, s25, s27
	s_add_i32 s35, s24, s7
	s_mov_b32 m0, s35
	s_nop 0
	global_load_lds_dwordx4 v132, s[22:23]
	s_add_i32 s35, s24, s10
	s_addk_i32 s35, 0x400
	s_mov_b32 m0, s35
	s_nop 0
	global_load_lds_dwordx4 v131, s[22:23]
	s_and_b64 s[22:23], exec, s[8:9]
	s_cselect_b32 s23, s26, s34
	s_cselect_b32 s22, s25, s27
	s_add_i32 s35, s24, s11
	s_addk_i32 s35, 0x800
	s_mov_b32 m0, s35
	s_nop 0
	global_load_lds_dwordx4 v130, s[22:23]
	s_add_i32 s35, s24, s12
	s_addk_i32 s35, 0xc00
	s_mov_b32 m0, s35
	s_nop 0
	global_load_lds_dwordx4 v129, s[22:23]
	s_add_i32 s35, s24, s13
	s_addk_i32 s35, 0x1000
	s_mov_b32 m0, s35
	s_nop 0
	global_load_lds_dwordx4 v133, s[22:23]
	s_waitcnt vmcnt(10)
	s_waitcnt lgkmcnt(0)
	s_barrier
; #define LAS __attribute__((address_space(3)))
; DI s16x4 vtr(const LAS char* p) { return __builtin_bit_cast(s16x4, __builtin_amdgcn_ds_read_tr16_b64_v4i16((LAS v4i16_t*)p)); }
; DI bf16x8 cat4(s16x4 lo, s16x4 hi) { return __builtin_shufflevector(lo, hi, 0, 1, 2, 3, 4, 5, 6, 7); }
; DI void attn_qk(const LAS char* kb, const bf16x8 (&qf)[4], bf16x8 (&pf)[4], float& l) {
;     ...
;     f32x16 st0 = MFMA32(k0[0], qf[0], zero), st1 = MFMA32(k1[0], qf[0], zero);
; #pragma unroll
;     for (int s = 1; s < 4; ++s) { st0 = MFMA32(k0[s], qf[s], st0); st1 = MFMA32(k1[s], qf[s], st1); }
;     SGB(0x100, 8); SGB(0x008, 8);
;     float sum = 0.f;
; #pragma unroll
;     for (int i = 0; i < 16; ++i) { const float e = __builtin_amdgcn_exp2f(st0[i]); st0[i] = e; sum += e; }
;     pf[0] = pack8(st0, 0); pf[1] = pack8(st0, 1);
; #pragma unroll
;     for (int i = 0; i < 16; ++i) { const float e = __builtin_amdgcn_exp2f(st1[i]); st1[i] = e; sum += e; }
;     pf[2] = pack8(st1, 0); pf[3] = pack8(st1, 1);
;     l += sum;
; }
; DI void attn_pv(const LAS char* vb, const bf16x8 (&pf)[4], f32x16 (&O)[4]) {
;     s16x4 va[8], vc[8];
; #pragma unroll
;     for (int ks = 0; ks < 4; ++ks) { va[2 * ks] = vtr(vb + ks * 16 * VRS); va[2 * ks + 1] = vtr(vb + (ks * 16 + 8) * VRS); }
; #pragma unroll
;     for (int ks = 0; ks < 4; ++ks) { vc[2 * ks] = vtr(vb + ks * 16 * VRS + 64); vc[2 * ks + 1] = vtr(vb + (ks * 16 + 8) * VRS + 64); }
; #pragma unroll
;     for (int ks = 0; ks < 4; ++ks) O[0] = MFMA32(cat4(va[2 * ks], va[2 * ks + 1]), pf[ks], O[0]);
; #pragma unroll
;     for (int ks = 0; ks < 4; ++ks) { va[2 * ks] = vtr(vb + ks * 16 * VRS + 128); va[2 * ks + 1] = vtr(vb + (ks * 16 + 8) * VRS + 128); }
;     SGB(0x100, 16); SGB(0x008, 4); SGB(0x100, 8);
; #pragma unroll
;     for (int ks = 0; ks < 4; ++ks) O[1] = MFMA32(cat4(vc[2 * ks], vc[2 * ks + 1]), pf[ks], O[1]);
; #pragma unroll
;     for (int ks = 0; ks < 4; ++ks) { vc[2 * ks] = vtr(vb + ks * 16 * VRS + 192); vc[2 * ks + 1] = vtr(vb + (ks * 16 + 8) * VRS + 192); }
;     SGB(0x008, 4); SGB(0x100, 8);
; #pragma unroll
;     for (int ks = 0; ks < 4; ++ks) O[2] = MFMA32(cat4(va[2 * ks], va[2 * ks + 1]), pf[ks], O[2]);
;     SGB(0x008, 4);
; #pragma unroll
;     for (int ks = 0; ks < 4; ++ks) O[3] = MFMA32(cat4(vc[2 * ks], vc[2 * ks + 1]), pf[ks], O[3]);
;     SGB(0x008, 4);
; }
	s_setprio 1
	v_mfma_f32_32x32x16_bf16 v[96:111], v[2:5], v[112:115], 0
	v_mfma_f32_32x32x16_bf16 v[96:111], v[6:9], v[116:119], v[96:111]
	v_mfma_f32_32x32x16_bf16 v[96:111], v[10:13], v[120:123], v[96:111]
	v_mfma_f32_32x32x16_bf16 v[96:111], v[136:139], v[124:127], v[96:111]
	s_nop 7
	s_nop 2
	v_mfma_f32_32x32x16_bf16 v[80:95], v[140:143], v[112:115], 0
	v_exp_f32_e32 v96, v96
	v_exp_f32_e32 v97, v97
	s_nop 0
	v_add_f32_e32 v15, v96, v97
	v_mfma_f32_32x32x16_bf16 v[80:95], v[144:147], v[116:119], v[80:95]
	v_exp_f32_e32 v98, v98
	v_exp_f32_e32 v99, v99
	v_cvt_pk_bf16_f32 v96, v96, v97
	v_add_f32_e32 v15, v98, v15
	v_mfma_f32_32x32x16_bf16 v[80:95], v[148:151], v[120:123], v[80:95]
	v_exp_f32_e32 v100, v100
	v_exp_f32_e32 v101, v101
	v_cvt_pk_bf16_f32 v97, v98, v99
	v_add_f32_e32 v15, v99, v15
	v_mfma_f32_32x32x16_bf16 v[80:95], v[196:199], v[124:127], v[80:95]
	v_exp_f32_e32 v102, v102
	v_exp_f32_e32 v103, v103
	v_cvt_pk_bf16_f32 v98, v100, v101
	v_cvt_pk_bf16_f32 v99, v102, v103
	s_nop 1
	v_mfma_f32_32x32x16_bf16 v[64:79], v[200:203], v[96:99], v[64:79]
	v_exp_f32_e32 v104, v104
	v_exp_f32_e32 v105, v105
	v_add_f32_e32 v15, v104, v15
	v_add_f32_e32 v15, v105, v15
	v_mfma_f32_32x32x16_bf16 v[48:63], v[204:207], v[96:99], v[48:63]
	v_exp_f32_e32 v106, v106
	v_exp_f32_e32 v107, v107
	v_cvt_pk_bf16_f32 v104, v104, v105
	v_add_f32_e32 v15, v106, v15
	v_mfma_f32_32x32x16_bf16 v[32:47], v[208:211], v[96:99], v[32:47]
	v_exp_f32_e32 v108, v108
	v_exp_f32_e32 v109, v109
	v_cvt_pk_bf16_f32 v105, v106, v107
	v_add_f32_e32 v15, v107, v15
	v_mfma_f32_32x32x16_bf16 v[16:31], v[212:215], v[96:99], v[16:31]
	v_exp_f32_e32 v110, v110
	v_exp_f32_e32 v111, v111
	v_cvt_pk_bf16_f32 v106, v108, v109
	v_cvt_pk_bf16_f32 v107, v110, v111
	s_nop 1
	v_mfma_f32_32x32x16_bf16 v[64:79], v[216:219], v[104:107], v[64:79]
	v_exp_f32_e32 v80, v80
	v_exp_f32_e32 v81, v81
	v_add_f32_e32 v15, v80, v15
	v_add_f32_e32 v15, v81, v15
	v_mfma_f32_32x32x16_bf16 v[48:63], v[220:223], v[104:107], v[48:63]
	v_exp_f32_e32 v82, v82
	v_exp_f32_e32 v83, v83
	v_cvt_pk_bf16_f32 v80, v80, v81
	v_add_f32_e32 v15, v82, v15
	v_mfma_f32_32x32x16_bf16 v[32:47], v[224:227], v[104:107], v[32:47]
	v_exp_f32_e32 v84, v84
	v_exp_f32_e32 v85, v85
	v_cvt_pk_bf16_f32 v81, v82, v83
	v_add_f32_e32 v15, v83, v15
	v_mfma_f32_32x32x16_bf16 v[16:31], v[228:231], v[104:107], v[16:31]
	v_exp_f32_e32 v86, v86
	v_exp_f32_e32 v87, v87
	v_cvt_pk_bf16_f32 v82, v84, v85
	v_cvt_pk_bf16_f32 v83, v86, v87
	s_nop 1
	v_mfma_f32_32x32x16_bf16 v[64:79], v[232:235], v[80:83], v[64:79]
	v_exp_f32_e32 v88, v88
	v_exp_f32_e32 v89, v89
	v_add_f32_e32 v15, v88, v15
	v_add_f32_e32 v15, v89, v15
	v_mfma_f32_32x32x16_bf16 v[48:63], v[236:239], v[80:83], v[48:63]
	v_exp_f32_e32 v90, v90
	v_exp_f32_e32 v91, v91
	v_cvt_pk_bf16_f32 v88, v88, v89
	v_add_f32_e32 v15, v90, v15
	v_mfma_f32_32x32x16_bf16 v[32:47], v[240:243], v[80:83], v[32:47]
	v_exp_f32_e32 v92, v92
	v_exp_f32_e32 v93, v93
	v_cvt_pk_bf16_f32 v89, v90, v91
	v_add_f32_e32 v15, v91, v15
	v_mfma_f32_32x32x16_bf16 v[16:31], v[244:247], v[80:83], v[16:31]
	v_exp_f32_e32 v94, v94
	v_exp_f32_e32 v95, v95
	v_cvt_pk_bf16_f32 v90, v92, v93
	v_cvt_pk_bf16_f32 v91, v94, v95
	s_nop 1
	v_mfma_f32_32x32x16_bf16 v[64:79], v[248:251], v[88:91], v[64:79]
	v_add_f32_e32 v15, v100, v15
	v_add_f32_e32 v15, v101, v15
	v_add_f32_e32 v15, v102, v15
	v_add_f32_e32 v15, v103, v15
	v_mfma_f32_32x32x16_bf16 v[48:63], v[156:159], v[88:91], v[48:63]
	v_add_f32_e32 v15, v108, v15
	v_add_f32_e32 v15, v109, v15
	v_add_f32_e32 v15, v110, v15
	v_add_f32_e32 v15, v111, v15
	v_mfma_f32_32x32x16_bf16 v[32:47], v[160:163], v[88:91], v[32:47]
	v_add_f32_e32 v15, v84, v15
	v_add_f32_e32 v15, v85, v15
	v_add_f32_e32 v15, v86, v15
	v_add_f32_e32 v15, v87, v15
	v_mfma_f32_32x32x16_bf16 v[16:31], v[164:167], v[88:91], v[16:31]
	v_add_f32_e32 v15, v92, v15
	v_add_f32_e32 v15, v93, v15
	v_add_f32_e32 v15, v94, v15
	v_add_f32_e32 v15, v95, v15
	v_add_f32_e32 v175, v175, v15
	s_setprio 0
	s_barrier
	s_branch .LBB0_744
